# scan loop waits de-serialized + dilated attention Q/K/V loads batched (one wait per MFMA group), flat->global in those loops
# baseline (speedup 1.0000x reference)
.LBB0_699:
	v_mul_hi_i32 v0, v191, s33
	v_lshrrev_b32_e32 v1, 31, v0
	v_ashrrev_i32_e32 v0, 7, v0
	v_add_u32_e32 v1, v0, v1
	s_movk_i32 s10, 0xfe60
	v_mad_i32_i24 v0, v1, s10, v191
	v_mul_hi_i32 v2, v0, s33
	v_lshrrev_b32_e32 v3, 31, v2
	v_ashrrev_i32_e32 v2, 4, v2
	v_add_u32_e32 v200, v2, v3
	s_movk_i32 s10, 0x19f
	v_lshlrev_b32_e32 v218, 6, v1
	v_cmp_lt_i32_e32 vcc, s10, v191
	v_lshlrev_b32_e32 v216, 7, v200
	v_mov_b32_e32 v217, v182
	s_and_saveexec_b64 s[10:11], vcc
	s_cbranch_execz .LBB0_703
	v_ashrrev_i32_e32 v217, 31, v216
	v_lshl_add_u64 v[2:3], v[216:217], 2, s[2:3]
	v_lshlrev_b32_e32 v4, 2, v178
	v_add_co_u32_e32 v2, vcc, v2, v4
	s_nop 1
	v_addc_co_u32_e32 v3, vcc, 0, v3, vcc
	v_add_co_u32_e32 v6, vcc, 0x1000, v2
	s_nop 1
	v_addc_co_u32_e32 v7, vcc, 0, v3, vcc
	global_load_dword v5, v[2:3], off
	global_load_dword v4, v[6:7], off
	s_mov_b32 s20, 0
	v_mov_b32_e32 v217, 0
	s_waitcnt vmcnt(0)
	v_add_f32_e32 v5, v4, v5
	s_nop 1
.Lscan_pre:
	v_readlane_b32 s12, v4, s20
	v_readlane_b32 s13, v5, s20
	s_add_i32 s20, s20, 1
	s_cmp_lt_u32 s20, 64
	v_add_f32_e32 v6, s12, v217
	v_max_f32_e32 v217, s13, v6
	s_cbranch_scc1 .Lscan_pre
	v_mov_b32_e32 v1, 0
.LBB0_703:
	s_or_b64 exec, exec, s[10:11]
	s_movk_i32 s10, 0xffcc
	v_mad_u64_u32 v[0:1], s[10:11], v200, s10, v[0:1]
	v_ashrrev_i32_e32 v1, 2, v0
	v_lshlrev_b32_e32 v202, 4, v1
	v_cmp_gt_i32_e32 vcc, 12, v1
	v_mad_i64_i32 v[2:3], s[10:11], v200, s56, 0
	s_nop 0
	v_cndmask_b32_e32 v4, 0, v202, vcc
	v_ashrrev_i32_e32 v5, 31, v4
	v_mad_i64_i32 v[4:5], s[10:11], v200, s56, v[4:5]
	v_or_b32_e32 v4, v4, v180
	v_or_b32_e32 v2, v2, v192
	v_ashrrev_i32_e32 v201, 31, v200
	v_lshlrev_b64 v[4:5], 8, v[4:5]
	v_lshlrev_b64 v[2:3], 8, v[2:3]
	v_lshlrev_b64 v[6:7], 15, v[200:201]
	v_lshl_add_u64 v[220:221], v[184:185], 0, v[4:5]
	v_lshl_add_u64 v[222:223], v[186:187], 0, v[2:3]
	v_lshl_add_u64 v[224:225], v[188:189], 0, v[6:7]
	v_mad_i64_i32 v[2:3], s[10:11], v218, s57, v[220:221]
	v_mad_i64_i32 v[6:7], s[10:11], v218, s57, v[222:223]
	s_movk_i32 s10, 0x1000
	s_nop 0
	v_add_co_u32_e32 v8, vcc, s10, v6
	v_ashrrev_i32_e32 v219, 31, v218
	s_nop 0
	v_addc_co_u32_e32 v9, vcc, 0, v7, vcc
	s_movk_i32 s10, 0x2000
	v_lshlrev_b64 v[4:5], 8, v[218:219]
	v_add_co_u32_e32 v10, vcc, s10, v6
	v_lshl_add_u64 v[4:5], v[224:225], 0, v[4:5]
	s_nop 0
	v_addc_co_u32_e32 v11, vcc, 0, v7, vcc
	s_waitcnt vmcnt(0)
	global_load_dwordx4 v[144:147], v[2:3], off
	global_load_dwordx4 v[120:123], v[2:3], off offset:64
	global_load_dwordx4 v[152:155], v[4:5], off
	global_load_dwordx4 v[128:131], v[4:5], off offset:64
	global_load_dwordx4 v[140:143], v[6:7], off
	global_load_dwordx4 v[108:111], v[6:7], off offset:64
	global_load_dwordx4 v[148:151], v[8:9], off
	global_load_dwordx4 v[124:127], v[8:9], off offset:64
	global_load_dwordx4 v[156:159], v[10:11], off
	global_load_dwordx4 v[136:139], v[10:11], off offset:64
	global_load_dwordx4 v[92:95], v[2:3], off offset:128
	global_load_dwordx4 v[72:75], v[2:3], off offset:192
	global_load_dwordx4 v[116:119], v[4:5], off offset:128
	global_load_dwordx4 v[76:79], v[4:5], off offset:192
	global_load_dwordx4 v[104:107], v[6:7], off offset:128
	global_load_dwordx4 v[60:63], v[6:7], off offset:192
	global_load_dwordx4 v[112:115], v[8:9], off offset:128
	global_load_dwordx4 v[56:59], v[8:9], off offset:192
	global_load_dwordx4 v[132:135], v[10:11], off offset:128
	global_load_dwordx4 v[48:51], v[10:11], off offset:192
	v_add_u32_e32 v2, v216, v218
	v_ashrrev_i32_e32 v3, 31, v2
	v_lshlrev_b64 v[226:227], 2, v[2:3]
	v_lshl_add_u64 v[2:3], s[4:5], 0, v[226:227]
	v_lshl_add_u64 v[4:5], s[2:3], 0, v[226:227]
	global_load_dword v234, v[2:3], off
	global_load_dword v235, v[4:5], off
	s_movk_i32 s10, 0x6800
	v_mad_i64_i32 v[228:229], s[10:11], v200, s10, 0
	v_or_b32_e32 v0, v0, v178
	v_ashrrev_i32_e32 v203, 31, v202
	v_cmp_eq_u32_e64 s[14:15], 0, v0
	v_add_u32_e32 v0, 0x19f, v191
	v_or_b32_e32 v2, v190, v228
	v_mov_b32_e32 v3, v229
	v_cmp_lt_i32_e64 s[12:13], 11, v1
	s_waitcnt vmcnt(0)
	v_cmp_gt_u32_e64 s[10:11], s58, v0
	v_mad_i64_i32 v[0:1], s[20:21], v218, s59, v[198:199]
	v_lshl_add_u64 v[2:3], v[2:3], 0, v[202:203]
	v_mad_u64_u32 v[230:231], s[20:21], v2, s60, v[0:1]
	s_mov_b32 s65, 0
	v_or_b32_e32 v233, 63, v218
	v_mad_i32_i24 v231, v3, s60, v231
	v_mov_b32_e32 v232, 0
	v_mov_b32_e32 v214, 0
	v_mov_b32_e32 v215, 0
	v_mov_b32_e32 v212, 0
	v_mov_b32_e32 v213, 0
	v_mov_b32_e32 v210, 0
	v_mov_b32_e32 v211, 0
	v_mov_b32_e32 v208, 0
	v_mov_b32_e32 v209, 0
	v_mov_b32_e32 v206, 0
	v_mov_b32_e32 v207, 0
	v_mov_b32_e32 v204, 0
	v_mov_b32_e32 v205, 0
	v_mov_b32_e32 v193, v217
.LBB0_704:
	v_lshl_add_u64 v[0:1], s[18:19], 0, v[230:231]
	s_mov_b32 s20, 0xc400000
	v_bfe_u32 v2, v206, 16, 1
	v_add_co_u32_e32 v0, vcc, s20, v0
	v_add3_u32 v2, v206, v2, s61
	s_nop 0
	v_addc_co_u32_e32 v1, vcc, 0, v1, vcc
	global_store_short_d16_hi v[0:1], v2, off
	v_bfe_u32 v2, v207, 16, 1
	v_add3_u32 v2, v207, v2, s61
	global_store_short_d16_hi v[0:1], v2, off offset:384
	v_bfe_u32 v2, v204, 16, 1
	v_add3_u32 v2, v204, v2, s61
	global_store_short_d16_hi v[0:1], v2, off offset:768
	v_bfe_u32 v2, v205, 16, 1
	v_add3_u32 v2, v205, v2, s61
	global_store_short_d16_hi v[0:1], v2, off offset:1152
	v_bfe_u32 v2, v210, 16, 1
	v_add3_u32 v2, v210, v2, s61
	global_store_short_d16_hi v[0:1], v2, off offset:32
	v_bfe_u32 v2, v211, 16, 1
	v_add3_u32 v2, v211, v2, s61
	global_store_short_d16_hi v[0:1], v2, off offset:416
	v_bfe_u32 v2, v208, 16, 1
	v_add3_u32 v2, v208, v2, s61
	global_store_short_d16_hi v[0:1], v2, off offset:800
	v_bfe_u32 v2, v209, 16, 1
	v_add3_u32 v2, v209, v2, s61
	global_store_short_d16_hi v[0:1], v2, off offset:1184
	v_bfe_u32 v2, v214, 16, 1
	v_add3_u32 v2, v214, v2, s61
	global_store_short_d16_hi v[0:1], v2, off offset:64
	v_bfe_u32 v2, v215, 16, 1
	v_add3_u32 v2, v215, v2, s61
	global_store_short_d16_hi v[0:1], v2, off offset:448
	v_bfe_u32 v2, v212, 16, 1
	v_add3_u32 v2, v212, v2, s61
	global_store_short_d16_hi v[0:1], v2, off offset:832
	v_bfe_u32 v2, v213, 16, 1
	v_add3_u32 v2, v213, v2, s61
	global_store_short_d16_hi v[0:1], v2, off offset:1216
	s_and_saveexec_b64 s[38:39], s[14:15]
	s_cbranch_execz .LBB0_706
	v_lshl_add_u64 v[0:1], s[18:19], 0, v[226:227]
	v_add_co_u32_e32 v2, vcc, 0x1fa4a000, v0
	s_nop 1
	v_addc_co_u32_e32 v3, vcc, 0, v1, vcc
	global_store_dword v[2:3], v193, off
	v_add_f32_e32 v2, v217, v232
	v_sub_f32_e32 v2, v2, v193
	v_mul_f32_e32 v2, 0x3fb8aa3b, v2
	v_exp_f32_e32 v2, v2
	v_add_co_u32_e32 v0, vcc, 0x1facf000, v0
	v_cndmask_b32_e64 v2, v2, 0, s[10:11]
	s_nop 0
	v_addc_co_u32_e32 v1, vcc, 0, v1, vcc
	global_store_dword v[0:1], v2, off
.LBB0_706:
	s_or_b64 exec, exec, s[38:39]
	v_add_u32_e32 v0, s65, v218
	v_add_u32_e32 v1, 1, v0
	v_cmp_lt_i32_e32 vcc, v0, v233
	s_nop 1
	v_cndmask_b32_e32 v160, v0, v1, vcc
	v_mad_i64_i32 v[4:5], s[20:21], v160, s57, v[222:223]
	v_add_co_u32_e32 v6, vcc, 0x1000, v4
	v_ashrrev_i32_e32 v161, 31, v160
	s_nop 0
	v_addc_co_u32_e32 v7, vcc, 0, v5, vcc
	v_lshlrev_b64 v[2:3], 8, v[160:161]
	v_add_co_u32_e32 v162, vcc, 0x2000, v4
	v_mad_i64_i32 v[0:1], s[20:21], v160, s57, v[220:221]
	v_lshl_add_u64 v[2:3], v[224:225], 0, v[2:3]
	v_addc_co_u32_e32 v163, vcc, 0, v5, vcc
	global_load_dwordx4 v[96:99], v[0:1], off
	global_load_dwordx4 v[100:103], v[2:3], off
	global_load_dwordx4 v[80:83], v[4:5], off
	global_load_dwordx4 v[84:87], v[6:7], off
	global_load_dwordx4 v[88:91], v[162:163], off
	global_load_dwordx4 v[64:67], v[0:1], off offset:64
	global_load_dwordx4 v[68:71], v[2:3], off offset:64
	global_load_dwordx4 v[52:55], v[4:5], off offset:64
	global_load_dwordx4 v[44:47], v[6:7], off offset:64
	global_load_dwordx4 v[40:43], v[162:163], off offset:64
	global_load_dwordx4 v[32:35], v[0:1], off offset:128
	global_load_dwordx4 v[36:39], v[2:3], off offset:128
	global_load_dwordx4 v[28:31], v[4:5], off offset:128
	global_load_dwordx4 v[24:27], v[6:7], off offset:128
	global_load_dwordx4 v[20:23], v[162:163], off offset:128
	global_load_dwordx4 v[12:15], v[0:1], off offset:192
	global_load_dwordx4 v[16:19], v[2:3], off offset:192
	global_load_dwordx4 v[8:11], v[4:5], off offset:192
	s_nop 0
	global_load_dwordx4 v[4:7], v[6:7], off offset:192
	s_nop 0
	global_load_dwordx4 v[0:3], v[162:163], off offset:192
	v_add_u32_e32 v160, v160, v216
	v_ashrrev_i32_e32 v161, 31, v160
	v_lshlrev_b64 v[160:161], 2, v[160:161]
	v_lshl_add_u64 v[162:163], s[4:5], 0, v[160:161]
	v_lshl_add_u64 v[160:161], s[2:3], 0, v[160:161]
	global_load_dword v201, v[162:163], off
	global_load_dword v219, v[160:161], off
	s_and_saveexec_b64 s[20:21], s[12:13]
	s_xor_b64 s[38:39], exec, s[20:21]
	s_cbranch_execz .LBB0_710
	v_mov_b32_e32 v183, v182
	v_mov_b64_e32 v[162:163], v[182:183]
	v_mov_b64_e32 v[160:161], v[182:183]
	s_and_saveexec_b64 s[42:43], s[8:9]
	s_cbranch_execz .LBB0_709
	s_nop 1
	v_mov_b64_e32 v[162:163], v[154:155]
	v_mov_b64_e32 v[160:161], v[152:153]

.LBB0_710:
	s_andn2_saveexec_b64 s[38:39], s[38:39]
	s_cbranch_execz .LBB0_712
	s_nop 1
	v_lshlrev_b32_e32 v160, 16, v144
	v_lshlrev_b32_e32 v161, 16, v152
	v_and_b32_e32 v152, 0xffff0000, v152
	v_and_b32_e32 v144, 0xffff0000, v144
	v_mul_f32_e32 v160, v161, v160
	v_mul_f32_e32 v144, v152, v144
	v_cvt_pk_bf16_f32 v160, v160, v144
	v_lshlrev_b32_e32 v144, 16, v145
	v_lshlrev_b32_e32 v152, 16, v153
	v_mul_f32_e32 v144, v152, v144
	v_and_b32_e32 v152, 0xffff0000, v153
	v_and_b32_e32 v145, 0xffff0000, v145
	v_mul_f32_e32 v145, v152, v145
	v_cvt_pk_bf16_f32 v161, v144, v145
	v_lshlrev_b32_e32 v144, 16, v146
	v_lshlrev_b32_e32 v145, 16, v154
	v_mul_f32_e32 v144, v145, v144
	v_and_b32_e32 v145, 0xffff0000, v154
	v_and_b32_e32 v146, 0xffff0000, v146
	v_mul_f32_e32 v145, v145, v146
	v_cvt_pk_bf16_f32 v162, v144, v145
	v_lshlrev_b32_e32 v144, 16, v147
	v_lshlrev_b32_e32 v145, 16, v155
	v_mul_f32_e32 v144, v145, v144
	v_and_b32_e32 v145, 0xffff0000, v155
	v_and_b32_e32 v146, 0xffff0000, v147
	v_mul_f32_e32 v145, v145, v146
	v_cvt_pk_bf16_f32 v163, v144, v145
.LBB0_712:
	s_or_b64 exec, exec, s[38:39]
	s_nop 1
	v_mfma_f32_16x16x32_bf16 v[140:143], v[160:163], v[140:143], 0
	v_mfma_f32_16x16x32_bf16 v[144:147], v[160:163], v[148:151], 0
	v_mfma_f32_16x16x32_bf16 v[148:151], v[160:163], v[156:159], 0
	s_and_saveexec_b64 s[20:21], s[12:13]
	s_xor_b64 s[38:39], exec, s[20:21]
	s_cbranch_execz .LBB0_716
	v_mov_b32_e32 v183, v182
	v_mov_b64_e32 v[154:155], v[182:183]
	v_mov_b64_e32 v[152:153], v[182:183]
	s_and_saveexec_b64 s[42:43], s[8:9]
	v_mov_b64_e32 v[154:155], v[130:131]
	v_mov_b64_e32 v[152:153], v[128:129]
	s_or_b64 exec, exec, s[42:43]

.LBB0_732:
	v_lshl_add_u64 v[50:51], v[228:229], 0, v[202:203]
	v_or_b32_e32 v49, v50, v190
	v_mad_u64_u32 v[56:57], s[20:21], v49, s60, v[194:195]
	v_mov_b32_e32 v50, v57
	v_mad_u64_u32 v[50:51], s[20:21], v51, s60, v[50:51]
	v_add_u32_e32 v48, s65, v218
	v_mov_b32_e32 v57, v50
	v_bfe_u32 v49, v206, 16, 1
	v_mad_i64_i32 v[50:51], s[20:21], v48, s59, v[56:57]
	v_add3_u32 v49, v206, v49, s61
	global_store_short_d16_hi v[50:51], v49, off
	v_bfe_u32 v49, v207, 16, 1
	v_add3_u32 v49, v207, v49, s61
	global_store_short_d16_hi v[50:51], v49, off offset:384
	v_bfe_u32 v49, v204, 16, 1
	v_add3_u32 v49, v204, v49, s61
	global_store_short_d16_hi v[50:51], v49, off offset:768
	v_bfe_u32 v49, v205, 16, 1
	v_add3_u32 v49, v205, v49, s61
	global_store_short_d16_hi v[50:51], v49, off offset:1152
	v_bfe_u32 v49, v210, 16, 1
	v_add3_u32 v49, v210, v49, s61
	global_store_short_d16_hi v[50:51], v49, off offset:32
	v_bfe_u32 v49, v211, 16, 1
	v_add3_u32 v49, v211, v49, s61
	global_store_short_d16_hi v[50:51], v49, off offset:416
	v_bfe_u32 v49, v208, 16, 1
	v_add3_u32 v49, v208, v49, s61
	global_store_short_d16_hi v[50:51], v49, off offset:800
	v_bfe_u32 v49, v209, 16, 1
	v_add3_u32 v49, v209, v49, s61
	global_store_short_d16_hi v[50:51], v49, off offset:1184
	v_bfe_u32 v49, v214, 16, 1
	v_add3_u32 v49, v214, v49, s61
	global_store_short_d16_hi v[50:51], v49, off offset:64
	v_bfe_u32 v49, v215, 16, 1
	v_add3_u32 v49, v215, v49, s61
	global_store_short_d16_hi v[50:51], v49, off offset:448
	v_bfe_u32 v49, v212, 16, 1
	v_add3_u32 v49, v212, v49, s61
	global_store_short_d16_hi v[50:51], v49, off offset:832
	v_bfe_u32 v49, v213, 16, 1
	v_add3_u32 v49, v213, v49, s61
	global_store_short_d16_hi v[50:51], v49, off offset:1216
	s_and_saveexec_b64 s[38:39], s[14:15]
	s_cbranch_execz .LBB0_734
	v_add_f32_e32 v50, v217, v232
	v_sub_f32_e32 v50, v50, v193
	v_mul_f32_e32 v50, 0x3fb8aa3b, v50
	v_add_u32_e32 v48, v48, v216
	v_exp_f32_e32 v56, v50
	v_ashrrev_i32_e32 v49, 31, v48
	v_lshlrev_b64 v[48:49], 2, v[48:49]
	v_lshl_add_u64 v[50:51], s[6:7], 0, v[48:49]
	global_store_dword v[50:51], v193, off
	v_cndmask_b32_e64 v50, v56, 0, s[10:11]
	v_lshl_add_u64 v[48:49], s[34:35], 0, v[48:49]
	global_store_dword v[48:49], v50, off

.LBB0_758:
	s_or_b64 exec, exec, s[12:13]
	v_mfma_f32_16x16x32_bf16 v[8:11], v[32:35], v[8:11], v[28:31]
	s_waitcnt vmcnt(0)
	v_mfma_f32_16x16x32_bf16 v[4:7], v[32:35], v[4:7], v[24:27]
	v_mfma_f32_16x16x32_bf16 v[0:3], v[32:35], v[0:3], v[20:23]
	s_and_saveexec_b64 s[12:13], s[10:11]
	s_cbranch_execz .LBB0_698
	v_add_f32_e32 v12, v193, v201
	v_add_f32_e32 v13, v201, v219
	v_max_f32_e32 v14, v12, v13
	v_sub_f32_e32 v13, v13, v14
	v_sub_f32_e32 v12, v12, v14
	v_mul_f32_e32 v13, 0x3fb8aa3b, v13
	v_mul_f32_e32 v12, 0x3fb8aa3b, v12
	v_exp_f32_e32 v13, v13
	v_exp_f32_e32 v12, v12
	v_mul_f32_e32 v14, v13, v0
	v_mul_f32_e32 v15, v13, v1
	v_mul_f32_e32 v8, v13, v8
	v_mad_i64_i32 v[0:1], s[10:11], v200, s64, v[202:203]
	v_fmac_f32_e32 v8, v12, v206
	v_or_b32_e32 v0, v0, v190
	v_mul_f32_e32 v16, v13, v2
	v_mul_f32_e32 v17, v13, v3
	v_mul_f32_e32 v9, v13, v9
	v_mad_u64_u32 v[2:3], s[10:11], v0, s60, v[196:197]
	v_bfe_u32 v0, v8, 16, 1
	v_fmac_f32_e32 v9, v12, v207
	v_mad_i32_i24 v3, v1, s60, v3
	v_add3_u32 v0, v8, v0, s61
	v_mul_f32_e32 v10, v13, v10
	global_store_short_d16_hi v[2:3], v0, off
	v_bfe_u32 v0, v9, 16, 1
	v_fmac_f32_e32 v10, v12, v204
	v_add3_u32 v0, v9, v0, s61
	v_mul_f32_e32 v11, v13, v11
	global_store_short_d16_hi v[2:3], v0, off offset:384
	v_bfe_u32 v0, v10, 16, 1
	v_fmac_f32_e32 v11, v12, v205
	v_add3_u32 v0, v10, v0, s61
	v_mul_f32_e32 v4, v13, v4
	global_store_short_d16_hi v[2:3], v0, off offset:768
	v_bfe_u32 v0, v11, 16, 1
	v_fmac_f32_e32 v4, v12, v210
	v_add3_u32 v0, v11, v0, s61
	v_mul_f32_e32 v5, v13, v5
	global_store_short_d16_hi v[2:3], v0, off offset:1152
	v_bfe_u32 v0, v4, 16, 1
	v_fmac_f32_e32 v5, v12, v211
	v_add3_u32 v0, v4, v0, s61
	v_mul_f32_e32 v6, v13, v6
	global_store_short_d16_hi v[2:3], v0, off offset:32
	v_bfe_u32 v0, v5, 16, 1
	v_fmac_f32_e32 v6, v12, v208
	v_add3_u32 v0, v5, v0, s61
	v_mul_f32_e32 v7, v13, v7
	global_store_short_d16_hi v[2:3], v0, off offset:416
	v_bfe_u32 v0, v6, 16, 1
	v_fmac_f32_e32 v7, v12, v209
	v_add3_u32 v0, v6, v0, s61
	global_store_short_d16_hi v[2:3], v0, off offset:800
	v_bfe_u32 v0, v7, 16, 1
	v_fmac_f32_e32 v14, v12, v214
	v_add3_u32 v0, v7, v0, s61
	global_store_short_d16_hi v[2:3], v0, off offset:1184
	v_bfe_u32 v0, v14, 16, 1
	v_fmac_f32_e32 v15, v12, v215
	v_add3_u32 v0, v14, v0, s61
	global_store_short_d16_hi v[2:3], v0, off offset:64
	v_bfe_u32 v0, v15, 16, 1
	v_fmac_f32_e32 v16, v12, v212
	v_add3_u32 v0, v15, v0, s61
	global_store_short_d16_hi v[2:3], v0, off offset:448
	v_bfe_u32 v0, v16, 16, 1
	v_fmac_f32_e32 v17, v12, v213
	v_add3_u32 v0, v16, v0, s61
	global_store_short_d16_hi v[2:3], v0, off offset:832
	v_bfe_u32 v0, v17, 16, 1
	v_add3_u32 v0, v17, v0, s61
	global_store_short_d16_hi v[2:3], v0, off offset:1216
	s_branch .LBB0_698

.LBB0_1987:
	v_lshrrev_b32_e32 v48, 4, v72
	v_and_b32_e32 v0, 15, v72
	v_bfe_u32 v1, v72, 2, 2
	v_cmp_eq_u32_e32 vcc, 1, v48
	v_cmp_gt_u32_e64 s[26:27], 16, v72
	v_lshlrev_b32_e32 v73, 1, v48
	v_cndmask_b32_e32 v0, v0, v1, vcc
	v_and_or_b32 v1, v71, 48, s81
	v_cndmask_b32_e64 v76, v0, 0, s[26:27]
	v_add_u32_e32 v0, s80, v71
	v_cndmask_b32_e32 v1, v70, v1, vcc
	v_cndmask_b32_e64 v75, v1, v0, s[26:27]
	v_or_b32_e32 v36, v75, v50
	v_lshlrev_b64 v[0:1], v73, v[36:37]
	v_or_b32_e32 v46, s4, v76
	v_mov_b32_e32 v47, s5
	v_lshl_add_u64 v[0:1], v[0:1], 0, v[46:47]
	v_lshl_or_b32 v74, v48, 2, s75
	v_lshlrev_b64 v[0:1], 11, v[0:1]
	v_lshl_add_u64 v[0:1], s[48:49], 0, v[0:1]
	v_lshlrev_b32_e32 v36, 7, v74
	v_lshl_add_u64 v[0:1], v[0:1], 0, v[36:37]
	v_add_u32_e32 v49, v75, v51
	v_lshl_add_u64 v[100:101], v[0:1], 0, v[44:45]
	v_lshl_add_u64 v[90:91], v[38:39], 0, v[36:37]
	v_max_i32_e32 v102, -16, v49
	v_max_i32_e32 v104, 0xffffffe0, v49
	v_max_i32_e32 v106, 0xffffffd0, v49
	v_max_i32_e32 v108, 0xffffffc0, v49
	v_max_i32_e32 v110, 0xffffffb0, v49
	v_max_i32_e32 v112, 0xffffffa0, v49
	v_max_i32_e32 v114, 0xffffff90, v49
	v_max_i32_e32 v116, 0xffffff80, v49
	v_add_u32_e32 v102, 16, v102
	v_add_u32_e32 v104, 32, v104
	v_add_u32_e32 v106, 48, v106
	v_add_u32_e32 v108, 64, v108
	v_add_u32_e32 v110, 0x50, v110
	v_add_u32_e32 v112, 0x60, v112
	v_add_u32_e32 v114, 0x70, v114
	v_add_u32_e32 v116, 0x80, v116
	v_add_u32_e32 v118, 0x90, v49
	v_lshlrev_b32_e32 v102, v73, v102
	v_lshlrev_b32_e32 v104, v73, v104
	v_lshlrev_b32_e32 v106, v73, v106
	v_lshlrev_b32_e32 v108, v73, v108
	v_lshlrev_b32_e32 v110, v73, v110
	v_lshlrev_b32_e32 v112, v73, v112
	v_lshlrev_b32_e32 v114, v73, v114
	v_lshlrev_b32_e32 v116, v73, v116
	v_lshlrev_b32_e32 v118, v73, v118
	v_add_u32_e32 v102, v102, v46
	v_add_u32_e32 v104, v104, v46
	v_add_u32_e32 v106, v106, v46
	v_add_u32_e32 v108, v108, v46
	v_add_u32_e32 v110, v110, v46
	v_add_u32_e32 v112, v112, v46
	v_add_u32_e32 v114, v114, v46
	v_add_u32_e32 v116, v116, v46
	v_add_u32_e32 v118, v118, v46
	global_load_dwordx4 v[120:123], v[100:101], off
	global_load_dwordx4 v[124:127], v[100:101], off offset:64
	v_mad_u64_u32 v[102:103], s[26:27], v102, s60, v[90:91]
	global_load_dwordx4 v[128:131], v[102:103], off
	global_load_dwordx4 v[132:135], v[102:103], off offset:64
	v_mad_u64_u32 v[104:105], s[26:27], v104, s60, v[90:91]
	global_load_dwordx4 v[136:139], v[104:105], off
	global_load_dwordx4 v[140:143], v[104:105], off offset:64
	v_mad_u64_u32 v[106:107], s[26:27], v106, s60, v[90:91]
	global_load_dwordx4 v[144:147], v[106:107], off
	global_load_dwordx4 v[148:151], v[106:107], off offset:64
	v_mad_u64_u32 v[108:109], s[26:27], v108, s60, v[90:91]
	global_load_dwordx4 v[152:155], v[108:109], off
	global_load_dwordx4 v[156:159], v[108:109], off offset:64
	v_mad_u64_u32 v[110:111], s[26:27], v110, s60, v[90:91]
	global_load_dwordx4 v[160:163], v[110:111], off
	global_load_dwordx4 v[164:167], v[110:111], off offset:64
	v_mad_u64_u32 v[112:113], s[26:27], v112, s60, v[90:91]
	global_load_dwordx4 v[168:171], v[112:113], off
	global_load_dwordx4 v[172:175], v[112:113], off offset:64
	v_mad_u64_u32 v[114:115], s[26:27], v114, s60, v[90:91]
	global_load_dwordx4 v[180:183], v[114:115], off
	global_load_dwordx4 v[184:187], v[114:115], off offset:64
	v_mad_u64_u32 v[116:117], s[26:27], v116, s60, v[90:91]
	global_load_dwordx4 v[188:191], v[116:117], off
	global_load_dwordx4 v[192:195], v[116:117], off offset:64
	v_mad_u64_u32 v[118:119], s[26:27], v118, s60, v[90:91]
	global_load_dwordx4 v[196:199], v[118:119], off
	global_load_dwordx4 v[200:203], v[118:119], off offset:64
	v_mov_b32_e32 v77, 0xf149f2ca
	v_mul_lo_u32 v36, v48, s59
	v_cmp_lt_i32_e64 s[26:27], s61, v49
	s_nop 3
	s_and_b64 s[30:31], s[10:11], s[26:27]
	s_waitcnt vmcnt(0)
	v_mfma_f32_16x16x32_bf16 v[32:35], v[120:123], v[128:131], 0
	v_mfma_f32_16x16x32_bf16 v[28:31], v[120:123], v[136:139], 0
	v_mfma_f32_16x16x32_bf16 v[24:27], v[120:123], v[144:147], 0
	v_mfma_f32_16x16x32_bf16 v[12:15], v[120:123], v[152:155], 0
	v_mfma_f32_16x16x32_bf16 v[0:3], v[120:123], v[160:163], 0
	v_mfma_f32_16x16x32_bf16 v[8:11], v[120:123], v[168:171], 0
	v_mfma_f32_16x16x32_bf16 v[16:19], v[120:123], v[180:183], 0
	v_mfma_f32_16x16x32_bf16 v[20:23], v[120:123], v[188:191], 0
	v_mfma_f32_16x16x32_bf16 v[4:7], v[120:123], v[196:199], 0
	v_mfma_f32_16x16x32_bf16 v[32:35], v[124:127], v[132:135], v[32:35]
	v_mfma_f32_16x16x32_bf16 v[28:31], v[124:127], v[140:143], v[28:31]
	v_mfma_f32_16x16x32_bf16 v[24:27], v[124:127], v[148:151], v[24:27]
	v_mfma_f32_16x16x32_bf16 v[12:15], v[124:127], v[156:159], v[12:15]
	v_mfma_f32_16x16x32_bf16 v[0:3], v[124:127], v[164:167], v[0:3]
	v_mfma_f32_16x16x32_bf16 v[8:11], v[124:127], v[172:175], v[8:11]
	v_mfma_f32_16x16x32_bf16 v[16:19], v[124:127], v[184:187], v[16:19]
	v_mfma_f32_16x16x32_bf16 v[20:23], v[124:127], v[192:195], v[20:23]
	v_mfma_f32_16x16x32_bf16 v[4:7], v[124:127], v[200:203], v[4:7]
	s_nop 7
	s_nop 1
	s_cmp_lg_u64 s[52:53], 0
	s_cbranch_scc0 .Ldil_skipv
	v_add_u32_e32 v100, s82, v74
	v_ashrrev_i32_e32 v101, 31, v100
	v_lshlrev_b64 v[100:101], 21, v[100:101]
	v_sub_u32_e32 v102, 14, v73
	v_lshlrev_b32_e32 v102, v102, v76
	v_lshlrev_b32_e32 v102, 1, v102
	v_mov_b32_e32 v103, 0
	v_lshl_add_u64 v[100:101], v[40:41], 0, v[100:101]
	v_lshl_add_u64 v[100:101], v[100:101], 0, v[102:103]
	v_add_u32_e32 v119, v57, v75
	v_mov_b32_e32 v212, 0x80000
	v_mov_b32_e32 v213, 0
	v_mov_b32_e32 v214, 0x100000
	v_mov_b32_e32 v215, 0
	v_mov_b32_e32 v216, 0x180000
	v_mov_b32_e32 v217, 0
	v_max_i32_e32 v204, 0, v119
	v_ashrrev_i32_e32 v205, 31, v204
	v_lshl_add_u64 v[204:205], v[204:205], 1, v[100:101]
	v_lshl_add_u64 v[206:207], v[204:205], 0, v[212:213]
	v_lshl_add_u64 v[208:209], v[204:205], 0, v[214:215]
	v_lshl_add_u64 v[210:211], v[204:205], 0, v[216:217]
	global_load_dwordx4 v[120:123], v[204:205], off
	global_load_dwordx4 v[124:127], v[206:207], off
	global_load_dwordx4 v[128:131], v[208:209], off
	global_load_dwordx4 v[132:135], v[210:211], off
	v_max_i32_e32 v204, 0xffffffe0, v119
	v_ashrrev_i32_e32 v205, 31, v204
	v_lshl_add_u64 v[204:205], v[204:205], 1, v[100:101]
	v_lshl_add_u64 v[206:207], v[204:205], 0, v[212:213]
	v_lshl_add_u64 v[208:209], v[204:205], 0, v[214:215]
	v_lshl_add_u64 v[210:211], v[204:205], 0, v[216:217]
	global_load_dwordx4 v[136:139], v[204:205], off offset:64
	global_load_dwordx4 v[140:143], v[206:207], off offset:64
	global_load_dwordx4 v[144:147], v[208:209], off offset:64
	global_load_dwordx4 v[148:151], v[210:211], off offset:64
	v_max_i32_e32 v204, 0xffffffc0, v119
	v_ashrrev_i32_e32 v205, 31, v204
	v_lshl_add_u64 v[204:205], v[204:205], 1, v[100:101]
	v_lshl_add_u64 v[206:207], v[204:205], 0, v[212:213]
	v_lshl_add_u64 v[208:209], v[204:205], 0, v[214:215]
	v_lshl_add_u64 v[210:211], v[204:205], 0, v[216:217]
	global_load_dwordx4 v[152:155], v[204:205], off offset:128
	global_load_dwordx4 v[156:159], v[206:207], off offset:128
	global_load_dwordx4 v[160:163], v[208:209], off offset:128
	global_load_dwordx4 v[164:167], v[210:211], off offset:128
	v_max_i32_e32 v204, 0xffffffa0, v119
	v_ashrrev_i32_e32 v205, 31, v204
	v_lshl_add_u64 v[204:205], v[204:205], 1, v[100:101]
	v_lshl_add_u64 v[206:207], v[204:205], 0, v[212:213]
	v_lshl_add_u64 v[208:209], v[204:205], 0, v[214:215]
	v_lshl_add_u64 v[210:211], v[204:205], 0, v[216:217]
	global_load_dwordx4 v[168:171], v[204:205], off offset:192
	global_load_dwordx4 v[172:175], v[206:207], off offset:192
	global_load_dwordx4 v[180:183], v[208:209], off offset:192
	global_load_dwordx4 v[184:187], v[210:211], off offset:192
	v_max_i32_e32 v204, 0xffffff80, v119
	v_ashrrev_i32_e32 v205, 31, v204
	v_lshl_add_u64 v[204:205], v[204:205], 1, v[100:101]
	v_lshl_add_u64 v[206:207], v[204:205], 0, v[212:213]
	v_lshl_add_u64 v[208:209], v[204:205], 0, v[214:215]
	v_lshl_add_u64 v[210:211], v[204:205], 0, v[216:217]
	global_load_dwordx4 v[188:191], v[204:205], off offset:256
	global_load_dwordx4 v[192:195], v[206:207], off offset:256
	global_load_dwordx4 v[196:199], v[208:209], off offset:256
	global_load_dwordx4 v[200:203], v[210:211], off offset:256
.Ldil_skipv:
	v_lshl_add_u32 v80, v60, 2, v36
	v_mov_b32_e32 v78, 0xf149f2ca
	s_and_saveexec_b64 s[28:29], s[30:31]
	s_cbranch_execz .LBB0_1989
	ds_read_b32 v78, v80 offset:576
	s_waitcnt lgkmcnt(0)
	v_add_f32_e32 v78, v32, v78

.LBB0_2084:
	v_bfe_u32 v48, v12, 16, 1
	v_add3_u32 v12, v12, v48, s70
	ds_write_b16_d16_hi v54, v12 offset:4688
	v_bfe_u32 v12, v16, 16, 1
	v_add3_u32 v12, v16, v12, s70
	ds_write_b16_d16_hi v54, v12 offset:4720
	v_bfe_u32 v12, v20, 16, 1
	v_add3_u32 v12, v20, v12, s70
	ds_write_b16_d16_hi v54, v12 offset:4752
	v_bfe_u32 v12, v24, 16, 1
	v_add3_u32 v12, v24, v12, s70
	ds_write_b16_d16_hi v54, v12 offset:4784
	v_bfe_u32 v12, v28, 16, 1
	v_add3_u32 v12, v28, v12, s70
	ds_write_b16_d16_hi v54, v12 offset:4816
	v_bfe_u32 v12, v32, 16, 1
	v_add3_u32 v12, v32, v12, s70
	ds_write_b16_d16_hi v54, v12 offset:4848
	v_bfe_u32 v12, v77, 16, 1
	v_add3_u32 v12, v77, v12, s70
	ds_write_b16_d16_hi v54, v12 offset:4880
	v_bfe_u32 v12, v78, 16, 1
	v_add3_u32 v12, v78, v12, s70
	ds_write_b16_d16_hi v54, v12 offset:4912
	v_bfe_u32 v12, v79, 16, 1
	v_add3_u32 v12, v79, v12, s70
	ds_write_b16 v54, v37 offset:4656
	ds_write_b16_d16_hi v54, v12 offset:4944
	ds_write_b16 v54, v37 offset:4992
	v_bfe_u32 v12, v1, 16, 1
	v_add3_u32 v1, v1, v12, s70
	ds_write_b16_d16_hi v54, v1 offset:5024
	v_bfe_u32 v1, v5, 16, 1
	v_add3_u32 v1, v5, v1, s70
	ds_write_b16_d16_hi v54, v1 offset:5056
	v_bfe_u32 v1, v13, 16, 1
	v_add3_u32 v1, v13, v1, s70
	ds_write_b16_d16_hi v54, v1 offset:5088
	v_bfe_u32 v1, v17, 16, 1
	v_add3_u32 v1, v17, v1, s70
	ds_write_b16_d16_hi v54, v1 offset:5120
	v_bfe_u32 v1, v21, 16, 1
	v_add3_u32 v1, v21, v1, s70
	ds_write_b16_d16_hi v54, v1 offset:5152
	v_bfe_u32 v1, v25, 16, 1
	v_add3_u32 v1, v25, v1, s70
	ds_write_b16_d16_hi v54, v1 offset:5184
	v_bfe_u32 v1, v29, 16, 1
	v_add3_u32 v1, v29, v1, s70
	ds_write_b16_d16_hi v54, v1 offset:5216
	v_bfe_u32 v1, v33, 16, 1
	v_add3_u32 v1, v33, v1, s70
	ds_write_b16_d16_hi v54, v1 offset:5248
	v_bfe_u32 v1, v36, 16, 1
	v_add3_u32 v1, v36, v1, s70
	ds_write_b16_d16_hi v54, v1 offset:5280
	ds_write_b16 v54, v37 offset:5328
	v_bfe_u32 v1, v14, 16, 1
	v_add3_u32 v1, v14, v1, s70
	ds_write_b16_d16_hi v54, v1 offset:5360
	v_bfe_u32 v1, v18, 16, 1
	v_add3_u32 v1, v18, v1, s70
	ds_write_b16_d16_hi v54, v1 offset:5392
	v_bfe_u32 v1, v22, 16, 1
	v_add3_u32 v1, v22, v1, s70
	ds_write_b16_d16_hi v54, v1 offset:5424
	v_bfe_u32 v1, v26, 16, 1
	v_add3_u32 v1, v26, v1, s70
	ds_write_b16_d16_hi v54, v1 offset:5456
	v_bfe_u32 v1, v30, 16, 1
	v_add3_u32 v1, v30, v1, s70
	ds_write_b16_d16_hi v54, v1 offset:5488
	v_bfe_u32 v1, v34, 16, 1
	v_add3_u32 v1, v34, v1, s70
	ds_write_b16_d16_hi v54, v1 offset:5520
	v_bfe_u32 v1, v89, 16, 1
	v_add3_u32 v1, v89, v1, s70
	ds_write_b16_d16_hi v54, v1 offset:5552
	v_bfe_u32 v1, v90, 16, 1
	v_add3_u32 v1, v90, v1, s70
	ds_write_b16_d16_hi v54, v1 offset:5584
	v_bfe_u32 v1, v91, 16, 1
	v_add3_u32 v1, v91, v1, s70
	ds_write_b16_d16_hi v54, v1 offset:5616
	ds_write_b16 v54, v37 offset:5664
	v_bfe_u32 v1, v3, 16, 1
	v_add3_u32 v1, v3, v1, s70
	ds_write_b16_d16_hi v54, v1 offset:5696
	v_bfe_u32 v1, v7, 16, 1
	v_add3_u32 v1, v7, v1, s70
	ds_write_b16_d16_hi v54, v1 offset:5728
	v_bfe_u32 v1, v15, 16, 1
	v_add3_u32 v1, v15, v1, s70
	ds_write_b16_d16_hi v54, v1 offset:5760
	v_bfe_u32 v1, v19, 16, 1
	v_add3_u32 v1, v19, v1, s70
	ds_write_b16_d16_hi v54, v1 offset:5792
	v_bfe_u32 v1, v23, 16, 1
	v_add3_u32 v1, v23, v1, s70
	ds_write_b16_d16_hi v54, v1 offset:5824
	v_bfe_u32 v1, v27, 16, 1
	v_add3_u32 v1, v27, v1, s70
	ds_write_b16_d16_hi v54, v1 offset:5856
	v_bfe_u32 v1, v31, 16, 1
	v_add3_u32 v1, v31, v1, s70
	ds_write_b16_d16_hi v54, v1 offset:5888
	v_bfe_u32 v1, v35, 16, 1
	v_add3_u32 v1, v35, v1, s70
	ds_write_b16_d16_hi v54, v1 offset:5920
	v_bfe_u32 v1, v49, 16, 1
	v_add3_u32 v1, v49, v1, s70
	ds_write_b16_d16_hi v54, v1 offset:5952
	ds_read_b128 v[100:103], v56 offset:4656
	ds_read_b128 v[104:107], v56 offset:4720
	ds_read_b128 v[108:111], v56 offset:4784
	ds_read_b128 v[112:115], v56 offset:4848
	ds_read_b128 v[116:119], v56 offset:4912
	s_waitcnt vmcnt(0) lgkmcnt(0)
	v_mfma_f32_16x16x32_bf16 v[12:15], v[100:103], v[120:123], 0
	v_mfma_f32_16x16x32_bf16 v[16:19], v[100:103], v[124:127], 0
	v_mfma_f32_16x16x32_bf16 v[28:31], v[100:103], v[128:131], 0
	v_mfma_f32_16x16x32_bf16 v[20:23], v[100:103], v[132:135], 0
	v_mfma_f32_16x16x32_bf16 v[12:15], v[104:107], v[136:139], v[12:15]
	v_mfma_f32_16x16x32_bf16 v[16:19], v[104:107], v[140:143], v[16:19]
	v_mfma_f32_16x16x32_bf16 v[28:31], v[104:107], v[144:147], v[28:31]
	v_mfma_f32_16x16x32_bf16 v[20:23], v[104:107], v[148:151], v[20:23]
	v_mfma_f32_16x16x32_bf16 v[12:15], v[108:111], v[152:155], v[12:15]
	v_mfma_f32_16x16x32_bf16 v[16:19], v[108:111], v[156:159], v[16:19]
	v_mfma_f32_16x16x32_bf16 v[28:31], v[108:111], v[160:163], v[28:31]
	v_mfma_f32_16x16x32_bf16 v[20:23], v[108:111], v[164:167], v[20:23]
	v_mfma_f32_16x16x32_bf16 v[12:15], v[112:115], v[168:171], v[12:15]
	v_mfma_f32_16x16x32_bf16 v[16:19], v[112:115], v[172:175], v[16:19]
	v_mfma_f32_16x16x32_bf16 v[28:31], v[112:115], v[180:183], v[28:31]
	v_mfma_f32_16x16x32_bf16 v[20:23], v[112:115], v[184:187], v[20:23]
	v_mfma_f32_16x16x32_bf16 v[12:15], v[116:119], v[188:191], v[12:15]
	v_mfma_f32_16x16x32_bf16 v[16:19], v[116:119], v[192:195], v[16:19]
	v_mfma_f32_16x16x32_bf16 v[28:31], v[116:119], v[196:199], v[28:31]
	v_mfma_f32_16x16x32_bf16 v[20:23], v[116:119], v[200:203], v[20:23]
	s_nop 7
	s_nop 1
	v_lshlrev_b32_e32 v1, 6, v74
	v_lshlrev_b32_e32 v36, 1, v1
	v_mov_b32_e32 v1, v37
	v_lshlrev_b64 v[0:1], v73, v[0:1]
	v_mul_f32_e32 v3, v8, v12
	v_lshl_add_u64 v[0:1], v[0:1], 0, v[46:47]
	v_bfe_u32 v5, v3, 16, 1
	v_add3_u32 v3, v3, v5, s70
	v_lshlrev_b64 v[0:1], 11, v[0:1]
	v_mov_b32_e32 v5, v37
	v_lshl_add_u64 v[24:25], v[42:43], 0, v[36:37]
	v_lshl_add_u64 v[0:1], v[24:25], 0, v[0:1]
	v_lshlrev_b64 v[4:5], v73, v[4:5]
	s_waitcnt vmcnt(0)
	global_store_short_d16_hi v[0:1], v3, off
	v_lshl_add_u64 v[4:5], v[4:5], 0, v[46:47]
	v_mul_f32_e32 v3, v9, v13
	v_bfe_u32 v7, v3, 16, 1
	v_lshlrev_b64 v[4:5], 11, v[4:5]
	v_add3_u32 v3, v3, v7, s70
	v_lshl_add_u64 v[4:5], v[24:25], 0, v[4:5]
	global_store_short_d16_hi v[4:5], v3, off
	v_mov_b32_e32 v3, v37
	v_lshlrev_b64 v[2:3], v73, v[2:3]
	v_lshl_add_u64 v[2:3], v[2:3], 0, v[46:47]
	v_mul_f32_e32 v7, v10, v14
	v_bfe_u32 v12, v7, 16, 1
	v_lshlrev_b64 v[2:3], 11, v[2:3]
	v_add3_u32 v7, v7, v12, s70
	v_lshl_add_u64 v[2:3], v[24:25], 0, v[2:3]
	global_store_short_d16_hi v[2:3], v7, off
	v_mov_b32_e32 v7, v37
	v_lshlrev_b64 v[6:7], v73, v[6:7]
	v_lshl_add_u64 v[6:7], v[6:7], 0, v[46:47]
	v_mul_f32_e32 v12, v11, v15
	v_bfe_u32 v13, v12, 16, 1
	v_lshlrev_b64 v[6:7], 11, v[6:7]
	v_add3_u32 v12, v12, v13, s70
	v_lshl_add_u64 v[6:7], v[24:25], 0, v[6:7]
	global_store_short_d16_hi v[6:7], v12, off
	v_mul_f32_e32 v12, v8, v16
	v_bfe_u32 v13, v12, 16, 1
	v_add3_u32 v12, v12, v13, s70
	global_store_short_d16_hi v[0:1], v12, off offset:32
	v_mul_f32_e32 v12, v9, v17
	v_bfe_u32 v13, v12, 16, 1
	v_add3_u32 v12, v12, v13, s70
	global_store_short_d16_hi v[4:5], v12, off offset:32
	v_mul_f32_e32 v12, v10, v18
	v_bfe_u32 v13, v12, 16, 1
	v_add3_u32 v12, v12, v13, s70
	global_store_short_d16_hi v[2:3], v12, off offset:32
	v_mul_f32_e32 v12, v11, v19
	v_bfe_u32 v13, v12, 16, 1
	v_add3_u32 v12, v12, v13, s70
	global_store_short_d16_hi v[6:7], v12, off offset:32
	v_mul_f32_e32 v12, v8, v28
	v_bfe_u32 v13, v12, 16, 1
	v_add3_u32 v12, v12, v13, s70
	global_store_short_d16_hi v[0:1], v12, off offset:64
	v_mul_f32_e32 v12, v9, v29
	v_bfe_u32 v13, v12, 16, 1
	v_add3_u32 v12, v12, v13, s70
	global_store_short_d16_hi v[4:5], v12, off offset:64
	v_mul_f32_e32 v12, v10, v30
	v_bfe_u32 v13, v12, 16, 1
	v_add3_u32 v12, v12, v13, s70
	global_store_short_d16_hi v[2:3], v12, off offset:64
	v_mul_f32_e32 v12, v11, v31
	v_bfe_u32 v13, v12, 16, 1
	v_add3_u32 v12, v12, v13, s70
	v_mul_f32_e32 v8, v8, v20
	global_store_short_d16_hi v[6:7], v12, off offset:64
	v_bfe_u32 v12, v8, 16, 1
	v_add3_u32 v8, v8, v12, s70
	global_store_short_d16_hi v[0:1], v8, off offset:96
	v_mul_f32_e32 v0, v9, v21
	v_bfe_u32 v1, v0, 16, 1
	v_add3_u32 v0, v0, v1, s70
	global_store_short_d16_hi v[4:5], v0, off offset:96
	v_mul_f32_e32 v0, v10, v22
	v_bfe_u32 v1, v0, 16, 1
	v_add3_u32 v0, v0, v1, s70
	global_store_short_d16_hi v[2:3], v0, off offset:96
	v_mul_f32_e32 v0, v11, v23
	v_bfe_u32 v1, v0, 16, 1
	v_add3_u32 v0, v0, v1, s70
	global_store_short_d16_hi v[6:7], v0, off offset:96
	s_branch .LBB0_1986
